# P8 deferred half-tile stores: epilogue keeps 8 of 16 bf16 output groups in spare VGPRs, next tile K-loop stores one group per iteration (flush at phase exit)
# speedup vs baseline: 1.0280x; 1.0058x over previous
.LBB0_867:
	s_lshl_b32 s12, s12, 5
	s_and_b32 s18, s12, 0x60
	s_mov_b64 s[12:13], 0x80
	s_add_i32 m0, s35, 0x18000
	v_lshl_add_u64 v[6:7], v[6:7], 0, s[12:13]
	s_ashr_i32 s46, s92, 31
	s_lshl_b32 s15, s14, 13
	s_lshl_b32 s19, s18, 7
	s_waitcnt vmcnt(2)
	s_barrier
	global_load_lds_dwordx4 v[6:7], off
	v_lshl_add_u64 v[4:5], v[4:5], 0, s[12:13]
	s_add_i32 m0, s35, 0x1a000
	s_add_i32 s47, s35, 0x8000
	s_add_i32 s48, s35, 0xa000
	global_load_lds_dwordx4 v[4:5], off
	v_lshl_add_u64 v[0:1], v[0:1], 0, s[12:13]
	s_mov_b32 m0, s47
	s_add_u32 s16, s38, 0x40080
	global_load_lds_dwordx4 v[0:1], off
	v_lshl_add_u64 v[0:1], v[2:3], 0, s[12:13]
	s_mov_b32 m0, s48
	s_addc_u32 s17, s39, 0
	global_load_lds_dwordx4 v[0:1], off
	s_add_i32 m0, s35, 0x1c000
	v_lshl_add_u64 v[0:1], s[16:17], 0, v[130:131]
	global_load_lds_dwordx4 v[0:1], off
	v_lshl_add_u64 v[0:1], s[16:17], 0, v[134:135]
	s_add_i32 m0, s35, 0x1e000
	s_sext_i32_i8 s56, s4
	global_load_lds_dwordx4 v[0:1], off
	v_and_b32_e32 v0, 15, v220
	v_lshlrev_b32_e32 v1, 1, v11
	v_lshlrev_b32_e32 v2, 6, v220
	s_movk_i32 s4, 0x3c0
	v_lshlrev_b32_e32 v3, 2, v220
	v_and_or_b32 v2, v2, s4, v1
	v_and_b32_e32 v3, 32, v3
	v_lshl_or_b32 v144, s14, 6, v0
	v_lshl_or_b32 v0, v0, 6, v1
	v_lshlrev_b32_e32 v1, 8, v220
	v_bitop3_b32 v145, s19, v2, v3 bitop3:0xf6
	v_and_b32_e32 v1, 0x38000, v1
	v_lshlrev_b32_e32 v2, 11, v10
	v_or3_b32 v1, v8, v1, v2
	v_add_u32_e32 v136, v1, v9
	v_lshlrev_b32_e32 v1, 4, v12
	s_waitcnt vmcnt(6)
	s_cmpk_lt_u32 s5, 0x100
	v_and_b32_e32 v1, 0x78000, v1
	v_bitop3_b32 v0, v0, s15, v3 bitop3:0xde
	s_cselect_b64 s[14:15], -1, 0
	v_or3_b32 v1, v8, v1, v2
	s_add_i32 s50, 0, 0x10000
	s_add_i32 s51, 0, 0x14000
	s_mov_b32 s49, s92
	v_or_b32_e32 v146, s18, v11
	v_mov_b32_e32 v137, v131
	v_add_u32_e32 v138, v1, v9
	v_mov_b32_e32 v139, v131
	v_add_u32_e32 v147, s50, v145
	v_add_u32_e32 v148, s51, v145
	v_add_u32_e32 v149, 0, v0
	s_add_u32 s16, s78, 0x2000
	s_addc_u32 s17, s79, 0
	s_add_u32 s18, s78, 0x802000
	s_addc_u32 s19, s79, 0
	s_mov_b32 s100, 0
	s_mov_b64 s[98:99], 0x800000
	s_barrier
	s_branch .LBB0_870

.LBB0_870:
	s_add_i32 s45, s45, 1
	s_mul_i32 s4, s45, s46
	s_mul_hi_u32 s5, s45, s49
	s_add_i32 s5, s5, s4
	s_mul_i32 s4, s45, s49
	s_add_u32 s28, s4, s2
	s_addc_u32 s29, s5, s33
	v_mov_b64_e32 v[0:1], 0x800
	v_mov_b64_e32 v[2:3], 0x7ff
	v_cmp_gt_i64_e32 vcc, s[28:29], v[2:3]
	v_cmp_lt_i64_e64 s[4:5], s[28:29], v[0:1]
	s_cbranch_vccnz .LBB0_876
	s_ashr_i32 s24, s28, 31
	s_lshr_b32 s24, s24, 29
	s_add_i32 s26, s28, s24
	s_and_b32 s24, s26, -8
	s_sub_i32 s27, s28, s24
	s_cmp_gt_i32 s27, -1
	s_mov_b64 s[24:25], -1
	s_cbranch_scc0 .LBB0_873
	s_lshl_b32 s28, s27, 8
	s_mov_b64 s[24:25], 0

.LBB0_877:
	s_cmp_eq_u32 s100, 0
	s_cbranch_scc1 .Ldhs8_idle
	s_cmp_lt_i32 s61, 6
	s_cbranch_scc0 .Ldhs8_hi
	s_cmp_lt_i32 s61, 2
	s_cbranch_scc0 .Ldhs8_q1
	s_cmp_lt_i32 s61, 0
	s_cbranch_scc0 .Ldhs8_g9
	global_store_dwordx4 v255, v[226:229], s[16:17]
	s_branch .Ldhs8_done
.Ldhs8_g9:
	global_store_dwordx4 v255, v[230:233], s[18:19]
	s_branch .Ldhs8_done
.Ldhs8_q1:
	s_cmp_lt_i32 s61, 4
	s_cbranch_scc0 .Ldhs8_g11
	global_store_dwordx4 v255, v[234:237], s[16:17] offset:1024
	s_branch .Ldhs8_done
.Ldhs8_g11:
	global_store_dwordx4 v255, v[238:241], s[18:19] offset:1024
	s_branch .Ldhs8_done
.Ldhs8_hi:
	s_cmp_lt_i32 s61, 10
	s_cbranch_scc0 .Ldhs8_q3
	s_cmp_lt_i32 s61, 8
	s_cbranch_scc0 .Ldhs8_g13
	global_store_dwordx4 v255, v[242:245], s[16:17] offset:2048
	s_branch .Ldhs8_done
.Ldhs8_g13:
	global_store_dwordx4 v255, v[246:249], s[18:19] offset:2048
	s_branch .Ldhs8_done
.Ldhs8_q3:
	s_cmp_lt_i32 s61, 12
	s_cbranch_scc0 .Ldhs8_g15
	global_store_dwordx4 v255, v[250:253], s[16:17] offset:3072
	s_branch .Ldhs8_done
.Ldhs8_g15:
	global_store_dwordx4 v255, v[140:143], s[18:19] offset:3072
	s_branch .Ldhs8_done
.Ldhs8_idle:
	global_load_ubyte v255, v221, s[16:17]
.Ldhs8_done:
	ds_read_b128 v[150:153], v147
	ds_read_b128 v[154:157], v147 offset:1024
	ds_read_b128 v[158:161], v147 offset:2048
	ds_read_b128 v[162:165], v147 offset:3072
	ds_read_b128 v[166:169], v148
	ds_read_b128 v[170:173], v148 offset:1024
	ds_read_b128 v[174:177], v148 offset:2048
	ds_read_b128 v[178:181], v148 offset:3072
	s_add_u32 s38, s36, 0xfffc0080
	s_addc_u32 s39, s37, -1
	s_cmp_eq_u32 s61, 12
	s_cselect_b32 s41, s27, s39
	s_cselect_b32 s40, s57, s38
	s_cselect_b32 s39, s25, s60
	s_cselect_b32 s38, s58, s59
	v_lshl_add_u64 v[214:215], s[36:37], 0, v[136:137]
	s_add_i32 m0, s35, 0xc000
	ds_read_b128 v[182:185], v149
	ds_read_b128 v[186:189], v149 offset:1024
	ds_read_b128 v[190:193], v149 offset:2048
	ds_read_b128 v[194:197], v149 offset:3072
	ds_read_b128 v[198:201], v149 offset:4096
	ds_read_b128 v[202:205], v149 offset:5120
	ds_read_b128 v[206:209], v149 offset:6144
	ds_read_b128 v[210:213], v149 offset:7168
	global_load_lds_dwordx4 v[214:215], off
	v_lshl_add_u64 v[214:215], s[36:37], 0, v[138:139]
	s_add_i32 m0, s35, 0xe000
	s_nop 0
	global_load_lds_dwordx4 v[214:215], off
	s_waitcnt vmcnt(9)
	s_waitcnt lgkmcnt(0)
	s_barrier
	s_setprio 1
	s_waitcnt lgkmcnt(0)
	v_mfma_f32_16x16x32_bf16 v[124:127], v[150:153], v[182:185], v[124:127]
	v_mfma_f32_16x16x32_bf16 v[120:123], v[158:161], v[182:185], v[120:123]
	v_mfma_f32_16x16x32_bf16 v[108:111], v[150:153], v[190:193], v[108:111]
	v_mfma_f32_16x16x32_bf16 v[104:107], v[158:161], v[190:193], v[104:107]
	v_mfma_f32_16x16x32_bf16 v[92:95], v[150:153], v[198:201], v[92:95]
	v_mfma_f32_16x16x32_bf16 v[88:91], v[158:161], v[198:201], v[88:91]
	v_mfma_f32_16x16x32_bf16 v[76:79], v[150:153], v[206:209], v[76:79]
	v_mfma_f32_16x16x32_bf16 v[72:75], v[158:161], v[206:209], v[72:75]
	v_mfma_f32_16x16x32_bf16 v[124:127], v[154:157], v[186:189], v[124:127]
	v_mfma_f32_16x16x32_bf16 v[120:123], v[162:165], v[186:189], v[120:123]
	v_mfma_f32_16x16x32_bf16 v[108:111], v[154:157], v[194:197], v[108:111]
	v_mfma_f32_16x16x32_bf16 v[104:107], v[162:165], v[194:197], v[104:107]
	v_mfma_f32_16x16x32_bf16 v[92:95], v[154:157], v[202:205], v[92:95]
	v_mfma_f32_16x16x32_bf16 v[88:91], v[162:165], v[202:205], v[88:91]
	v_mfma_f32_16x16x32_bf16 v[76:79], v[154:157], v[210:213], v[76:79]
	v_mfma_f32_16x16x32_bf16 v[72:75], v[162:165], v[210:213], v[72:75]
	s_setprio 0
	s_setprio 1
	v_mfma_f32_16x16x32_bf16 v[116:119], v[166:169], v[182:185], v[116:119]
	v_mfma_f32_16x16x32_bf16 v[112:115], v[174:177], v[182:185], v[112:115]
	v_mfma_f32_16x16x32_bf16 v[100:103], v[166:169], v[190:193], v[100:103]
	v_mfma_f32_16x16x32_bf16 v[96:99], v[174:177], v[190:193], v[96:99]
	v_mfma_f32_16x16x32_bf16 v[84:87], v[166:169], v[198:201], v[84:87]
	v_mfma_f32_16x16x32_bf16 v[80:83], v[174:177], v[198:201], v[80:83]
	v_mfma_f32_16x16x32_bf16 v[68:71], v[166:169], v[206:209], v[68:71]
	v_mfma_f32_16x16x32_bf16 v[64:67], v[174:177], v[206:209], v[64:67]
	v_mfma_f32_16x16x32_bf16 v[116:119], v[170:173], v[186:189], v[116:119]
	v_mfma_f32_16x16x32_bf16 v[112:115], v[178:181], v[186:189], v[112:115]
	v_mfma_f32_16x16x32_bf16 v[100:103], v[170:173], v[194:197], v[100:103]
	v_mfma_f32_16x16x32_bf16 v[96:99], v[178:181], v[194:197], v[96:99]
	v_mfma_f32_16x16x32_bf16 v[84:87], v[170:173], v[202:205], v[84:87]
	v_mfma_f32_16x16x32_bf16 v[80:83], v[178:181], v[202:205], v[80:83]
	v_mfma_f32_16x16x32_bf16 v[68:71], v[170:173], v[210:213], v[68:71]
	v_mfma_f32_16x16x32_bf16 v[64:67], v[178:181], v[210:213], v[64:67]
	s_setprio 0
	s_barrier
	s_add_i32 s62, s50, s3
	v_lshl_add_u64 v[214:215], s[38:39], 0, v[130:131]
	s_mov_b32 m0, s62
	ds_read_b128 v[182:185], v149 offset:16384
	ds_read_b128 v[186:189], v149 offset:17408
	ds_read_b128 v[190:193], v149 offset:18432
	ds_read_b128 v[194:197], v149 offset:19456
	ds_read_b128 v[198:201], v149 offset:20480
	ds_read_b128 v[202:205], v149 offset:21504
	ds_read_b128 v[206:209], v149 offset:22528
	ds_read_b128 v[210:213], v149 offset:23552
	global_load_lds_dwordx4 v[214:215], off
	s_add_i32 m0, s62, 0x2000
	s_add_u32 s62, s38, 0x40000
	v_lshl_add_u64 v[216:217], s[38:39], 0, v[134:135]
	s_addc_u32 s63, s39, 0
	s_add_i32 s64, s51, s3
	global_load_lds_dwordx4 v[216:217], off
	v_lshl_add_u64 v[218:219], s[62:63], 0, v[130:131]
	s_mov_b32 m0, s64
	v_lshl_add_u64 v[222:223], s[40:41], 0, v[132:133]
	global_load_lds_dwordx4 v[218:219], off
	v_lshl_add_u64 v[218:219], s[62:63], 0, v[134:135]
	s_add_i32 m0, s64, 0x2000
	s_nop 0
	global_load_lds_dwordx4 v[218:219], off
	v_lshl_add_u64 v[218:219], s[40:41], 0, v[128:129]
	s_mov_b32 m0, s35
	s_nop 0
	global_load_lds_dwordx4 v[218:219], off
	s_mov_b32 m0, s42
	s_nop 0
	global_load_lds_dwordx4 v[222:223], off
	s_waitcnt vmcnt(9)
	s_waitcnt lgkmcnt(0)
	s_barrier
	s_setprio 1
	s_waitcnt lgkmcnt(0)
	v_mfma_f32_16x16x32_bf16 v[60:63], v[150:153], v[182:185], v[60:63]
	v_mfma_f32_16x16x32_bf16 v[56:59], v[158:161], v[182:185], v[56:59]
	v_mfma_f32_16x16x32_bf16 v[44:47], v[150:153], v[190:193], v[44:47]
	v_mfma_f32_16x16x32_bf16 v[40:43], v[158:161], v[190:193], v[40:43]
	v_mfma_f32_16x16x32_bf16 v[28:31], v[150:153], v[198:201], v[28:31]
	v_mfma_f32_16x16x32_bf16 v[24:27], v[158:161], v[198:201], v[24:27]
	v_mfma_f32_16x16x32_bf16 v[12:15], v[150:153], v[206:209], v[12:15]
	v_mfma_f32_16x16x32_bf16 v[8:11], v[158:161], v[206:209], v[8:11]
	v_mfma_f32_16x16x32_bf16 v[60:63], v[154:157], v[186:189], v[60:63]
	v_mfma_f32_16x16x32_bf16 v[56:59], v[162:165], v[186:189], v[56:59]
	v_mfma_f32_16x16x32_bf16 v[44:47], v[154:157], v[194:197], v[44:47]
	v_mfma_f32_16x16x32_bf16 v[40:43], v[162:165], v[194:197], v[40:43]
	v_mfma_f32_16x16x32_bf16 v[28:31], v[154:157], v[202:205], v[28:31]
	v_mfma_f32_16x16x32_bf16 v[24:27], v[162:165], v[202:205], v[24:27]
	v_mfma_f32_16x16x32_bf16 v[12:15], v[154:157], v[210:213], v[12:15]
	v_mfma_f32_16x16x32_bf16 v[8:11], v[162:165], v[210:213], v[8:11]
	s_setprio 0
	s_setprio 1
	v_mfma_f32_16x16x32_bf16 v[52:55], v[166:169], v[182:185], v[52:55]
	v_mfma_f32_16x16x32_bf16 v[48:51], v[174:177], v[182:185], v[48:51]
	v_mfma_f32_16x16x32_bf16 v[36:39], v[166:169], v[190:193], v[36:39]
	v_mfma_f32_16x16x32_bf16 v[32:35], v[174:177], v[190:193], v[32:35]
	v_mfma_f32_16x16x32_bf16 v[20:23], v[166:169], v[198:201], v[20:23]
	v_mfma_f32_16x16x32_bf16 v[16:19], v[174:177], v[198:201], v[16:19]
	v_mfma_f32_16x16x32_bf16 v[4:7], v[166:169], v[206:209], v[4:7]
	v_mfma_f32_16x16x32_bf16 v[0:3], v[174:177], v[206:209], v[0:3]
	v_mfma_f32_16x16x32_bf16 v[52:55], v[170:173], v[186:189], v[52:55]
	v_mfma_f32_16x16x32_bf16 v[48:51], v[178:181], v[186:189], v[48:51]
	v_mfma_f32_16x16x32_bf16 v[36:39], v[170:173], v[194:197], v[36:39]
	v_mfma_f32_16x16x32_bf16 v[32:35], v[178:181], v[194:197], v[32:35]
	v_mfma_f32_16x16x32_bf16 v[20:23], v[170:173], v[202:205], v[20:23]
	v_mfma_f32_16x16x32_bf16 v[16:19], v[178:181], v[202:205], v[16:19]
	v_mfma_f32_16x16x32_bf16 v[4:7], v[170:173], v[210:213], v[4:7]
	v_mfma_f32_16x16x32_bf16 v[0:3], v[178:181], v[210:213], v[0:3]
	s_setprio 0
	s_barrier
	s_add_i32 s62, 0, 0x18000
	s_add_i32 s63, 0, 0x1c000
	v_add_u32_e32 v162, s62, v145
	v_add_u32_e32 v178, s63, v145
	ds_read_b128 v[150:153], v162
	ds_read_b128 v[154:157], v162 offset:1024
	ds_read_b128 v[158:161], v162 offset:2048
	ds_read_b128 v[162:165], v162 offset:3072
	ds_read_b128 v[166:169], v178
	ds_read_b128 v[170:173], v178 offset:1024
	ds_read_b128 v[174:177], v178 offset:2048
	ds_read_b128 v[178:181], v178 offset:3072
	s_add_u32 s40, s40, 0x40000
	s_addc_u32 s41, s41, 0
	s_mov_b32 m0, s43
	v_lshl_add_u64 v[224:225], s[40:41], 0, v[128:129]
	ds_read_b128 v[182:185], v149 offset:32768
	ds_read_b128 v[186:189], v149 offset:33792
	ds_read_b128 v[190:193], v149 offset:34816
	ds_read_b128 v[194:197], v149 offset:35840
	ds_read_b128 v[198:201], v149 offset:36864
	ds_read_b128 v[202:205], v149 offset:37888
	ds_read_b128 v[206:209], v149 offset:38912
	ds_read_b128 v[210:213], v149 offset:39936
	global_load_lds_dwordx4 v[224:225], off
	v_lshl_add_u64 v[224:225], s[40:41], 0, v[132:133]
	s_mov_b32 m0, s44
	s_nop 0
	global_load_lds_dwordx4 v[224:225], off
	s_waitcnt vmcnt(8)
	s_waitcnt lgkmcnt(0)
	s_barrier
	s_setprio 1
	s_waitcnt lgkmcnt(0)
	v_mfma_f32_16x16x32_bf16 v[124:127], v[150:153], v[182:185], v[124:127]
	v_mfma_f32_16x16x32_bf16 v[120:123], v[158:161], v[182:185], v[120:123]
	v_mfma_f32_16x16x32_bf16 v[108:111], v[150:153], v[190:193], v[108:111]
	v_mfma_f32_16x16x32_bf16 v[104:107], v[158:161], v[190:193], v[104:107]
	v_mfma_f32_16x16x32_bf16 v[92:95], v[150:153], v[198:201], v[92:95]
	v_mfma_f32_16x16x32_bf16 v[88:91], v[158:161], v[198:201], v[88:91]
	v_mfma_f32_16x16x32_bf16 v[76:79], v[150:153], v[206:209], v[76:79]
	v_mfma_f32_16x16x32_bf16 v[72:75], v[158:161], v[206:209], v[72:75]
	v_mfma_f32_16x16x32_bf16 v[124:127], v[154:157], v[186:189], v[124:127]
	v_mfma_f32_16x16x32_bf16 v[120:123], v[162:165], v[186:189], v[120:123]
	v_mfma_f32_16x16x32_bf16 v[108:111], v[154:157], v[194:197], v[108:111]
	v_mfma_f32_16x16x32_bf16 v[104:107], v[162:165], v[194:197], v[104:107]
	v_mfma_f32_16x16x32_bf16 v[92:95], v[154:157], v[202:205], v[92:95]
	v_mfma_f32_16x16x32_bf16 v[88:91], v[162:165], v[202:205], v[88:91]
	v_mfma_f32_16x16x32_bf16 v[76:79], v[154:157], v[210:213], v[76:79]
	v_mfma_f32_16x16x32_bf16 v[72:75], v[162:165], v[210:213], v[72:75]
	s_setprio 0
	s_setprio 1
	v_mfma_f32_16x16x32_bf16 v[116:119], v[166:169], v[182:185], v[116:119]
	v_mfma_f32_16x16x32_bf16 v[112:115], v[174:177], v[182:185], v[112:115]
	v_mfma_f32_16x16x32_bf16 v[100:103], v[166:169], v[190:193], v[100:103]
	v_mfma_f32_16x16x32_bf16 v[96:99], v[174:177], v[190:193], v[96:99]
	v_mfma_f32_16x16x32_bf16 v[84:87], v[166:169], v[198:201], v[84:87]
	v_mfma_f32_16x16x32_bf16 v[80:83], v[174:177], v[198:201], v[80:83]
	v_mfma_f32_16x16x32_bf16 v[68:71], v[166:169], v[206:209], v[68:71]
	v_mfma_f32_16x16x32_bf16 v[64:67], v[174:177], v[206:209], v[64:67]
	v_mfma_f32_16x16x32_bf16 v[116:119], v[170:173], v[186:189], v[116:119]
	v_mfma_f32_16x16x32_bf16 v[112:115], v[178:181], v[186:189], v[112:115]
	v_mfma_f32_16x16x32_bf16 v[100:103], v[170:173], v[194:197], v[100:103]
	v_mfma_f32_16x16x32_bf16 v[96:99], v[178:181], v[194:197], v[96:99]
	v_mfma_f32_16x16x32_bf16 v[84:87], v[170:173], v[202:205], v[84:87]
	v_mfma_f32_16x16x32_bf16 v[80:83], v[178:181], v[202:205], v[80:83]
	v_mfma_f32_16x16x32_bf16 v[68:71], v[170:173], v[210:213], v[68:71]
	v_mfma_f32_16x16x32_bf16 v[64:67], v[178:181], v[210:213], v[64:67]
	s_setprio 0
	s_barrier
	s_add_i32 s40, s62, s3
	v_lshl_add_u64 v[214:215], v[214:215], 0, s[12:13]
	s_mov_b32 m0, s40
	ds_read_b128 v[182:185], v149 offset:49152
	ds_read_b128 v[186:189], v149 offset:50176
	ds_read_b128 v[190:193], v149 offset:51200
	ds_read_b128 v[194:197], v149 offset:52224
	ds_read_b128 v[198:201], v149 offset:53248
	ds_read_b128 v[202:205], v149 offset:54272
	ds_read_b128 v[206:209], v149 offset:55296
	ds_read_b128 v[210:213], v149 offset:56320
	global_load_lds_dwordx4 v[214:215], off
	s_add_i32 m0, s40, 0x2000
	s_add_u32 s38, s38, 0x40080
	v_lshl_add_u64 v[214:215], v[216:217], 0, s[12:13]
	s_addc_u32 s39, s39, 0
	s_add_i32 s40, s63, s3
	global_load_lds_dwordx4 v[214:215], off
	v_lshl_add_u64 v[214:215], s[38:39], 0, v[130:131]
	s_mov_b32 m0, s40
	s_nop 0
	global_load_lds_dwordx4 v[214:215], off
	v_lshl_add_u64 v[214:215], s[38:39], 0, v[134:135]
	s_add_i32 m0, s40, 0x2000
	s_nop 0
	global_load_lds_dwordx4 v[214:215], off
	v_lshl_add_u64 v[214:215], v[218:219], 0, s[12:13]
	s_mov_b32 m0, s47
	s_nop 0
	global_load_lds_dwordx4 v[214:215], off
	v_lshl_add_u64 v[214:215], v[222:223], 0, s[12:13]
	s_mov_b32 m0, s48
	s_nop 0
	global_load_lds_dwordx4 v[214:215], off
	s_waitcnt vmcnt(8)
	s_waitcnt lgkmcnt(0)
	s_barrier
	s_setprio 1
	s_waitcnt lgkmcnt(0)
	v_mfma_f32_16x16x32_bf16 v[60:63], v[150:153], v[182:185], v[60:63]
	v_mfma_f32_16x16x32_bf16 v[56:59], v[158:161], v[182:185], v[56:59]
	v_mfma_f32_16x16x32_bf16 v[44:47], v[150:153], v[190:193], v[44:47]
	v_mfma_f32_16x16x32_bf16 v[40:43], v[158:161], v[190:193], v[40:43]
	v_mfma_f32_16x16x32_bf16 v[28:31], v[150:153], v[198:201], v[28:31]
	v_mfma_f32_16x16x32_bf16 v[24:27], v[158:161], v[198:201], v[24:27]
	v_mfma_f32_16x16x32_bf16 v[12:15], v[150:153], v[206:209], v[12:15]
	v_mfma_f32_16x16x32_bf16 v[8:11], v[158:161], v[206:209], v[8:11]
	v_mfma_f32_16x16x32_bf16 v[60:63], v[154:157], v[186:189], v[60:63]
	v_mfma_f32_16x16x32_bf16 v[56:59], v[162:165], v[186:189], v[56:59]
	v_mfma_f32_16x16x32_bf16 v[44:47], v[154:157], v[194:197], v[44:47]
	v_mfma_f32_16x16x32_bf16 v[40:43], v[162:165], v[194:197], v[40:43]
	v_mfma_f32_16x16x32_bf16 v[28:31], v[154:157], v[202:205], v[28:31]
	v_mfma_f32_16x16x32_bf16 v[24:27], v[162:165], v[202:205], v[24:27]
	v_mfma_f32_16x16x32_bf16 v[12:15], v[154:157], v[210:213], v[12:15]
	v_mfma_f32_16x16x32_bf16 v[8:11], v[162:165], v[210:213], v[8:11]
	s_setprio 0
	s_setprio 1
	v_mfma_f32_16x16x32_bf16 v[52:55], v[166:169], v[182:185], v[52:55]
	v_mfma_f32_16x16x32_bf16 v[48:51], v[174:177], v[182:185], v[48:51]
	v_mfma_f32_16x16x32_bf16 v[36:39], v[166:169], v[190:193], v[36:39]
	v_mfma_f32_16x16x32_bf16 v[32:35], v[174:177], v[190:193], v[32:35]
	v_mfma_f32_16x16x32_bf16 v[20:23], v[166:169], v[198:201], v[20:23]
	v_mfma_f32_16x16x32_bf16 v[16:19], v[174:177], v[198:201], v[16:19]
	v_mfma_f32_16x16x32_bf16 v[4:7], v[166:169], v[206:209], v[4:7]
	v_mfma_f32_16x16x32_bf16 v[0:3], v[174:177], v[206:209], v[0:3]
	v_mfma_f32_16x16x32_bf16 v[52:55], v[170:173], v[186:189], v[52:55]
	v_mfma_f32_16x16x32_bf16 v[48:51], v[178:181], v[186:189], v[48:51]
	v_mfma_f32_16x16x32_bf16 v[36:39], v[170:173], v[194:197], v[36:39]
	v_mfma_f32_16x16x32_bf16 v[32:35], v[178:181], v[194:197], v[32:35]
	v_mfma_f32_16x16x32_bf16 v[20:23], v[170:173], v[202:205], v[20:23]
	v_mfma_f32_16x16x32_bf16 v[16:19], v[178:181], v[202:205], v[16:19]
	v_mfma_f32_16x16x32_bf16 v[4:7], v[170:173], v[210:213], v[4:7]
	v_mfma_f32_16x16x32_bf16 v[0:3], v[178:181], v[210:213], v[0:3]
	s_setprio 0
	s_barrier
	s_add_i32 s61, s61, 2
	s_add_u32 s36, s36, 0x100
	s_addc_u32 s37, s37, 0
	s_add_u32 s59, s59, 0x100
	s_addc_u32 s60, s60, 0
	s_cmp_gt_u32 s61, 13
	s_cbranch_scc0 .LBB0_877
	s_and_b64 vcc, exec, s[14:15]
	s_cbranch_vccz .LBB0_880
	s_barrier
.LBB0_880:
	v_lshl_add_u32 v150, s34, 8, v144
	v_lshl_or_b32 v152, s56, 8, v146
	v_ashrrev_i32_e32 v151, 31, v150
	v_max_f32_e32 v124, 0, v124
	v_max_f32_e32 v120, 0, v120
	v_max_f32_e32 v125, 0, v125
	v_max_f32_e32 v121, 0, v121
	v_max_f32_e32 v126, 0, v126
	v_max_f32_e32 v127, 0, v127
	v_ashrrev_i32_e32 v153, 31, v152
	v_lshlrev_b64 v[154:155], 6, v[150:151]
	v_pk_mul_f32 v[124:125], v[124:125], v[124:125]
	v_pk_mul_f32 v[120:121], v[120:121], v[120:121]
	v_max_f32_e32 v122, 0, v122
	v_max_f32_e32 v123, 0, v123
	v_pk_mul_f32 v[126:127], v[126:127], v[126:127]
	v_pk_mul_f32 v[156:157], v[122:123], v[122:123]
	v_cvt_pk_bf16_f32 v122, v124, v125
	v_cvt_pk_bf16_f32 v123, v126, v127
	v_cvt_pk_bf16_f32 v124, v120, v121
	v_lshl_add_u64 v[120:121], s[78:79], 0, v[154:155]
	v_and_b32_e32 v126, 0xfe0, v152
	v_and_b32_e32 v127, 31, v152
	v_lshlrev_b32_e32 v126, 16, v126
	v_lshl_or_b32 v126, v127, 1, v126
	v_add_u32_e32 v255, v154, v126
	v_mov_b32_e32 v127, 0
	v_cvt_pk_bf16_f32 v125, v156, v157
	v_lshl_add_u64 v[120:121], v[120:121], 0, v[126:127]
	v_max_f32_e32 v112, 0, v112
	v_max_f32_e32 v113, 0, v113
	global_store_dwordx4 v[120:121], v[122:125], off
	s_nop 1
	v_pk_mul_f32 v[122:123], v[112:113], v[112:113]
	v_max_f32_e32 v114, 0, v114
	v_max_f32_e32 v116, 0, v116
	v_max_f32_e32 v117, 0, v117
	v_max_f32_e32 v112, 0, v118
	v_max_f32_e32 v113, 0, v119
	v_max_f32_e32 v115, 0, v115
	v_pk_mul_f32 v[116:117], v[116:117], v[116:117]
	v_pk_mul_f32 v[118:119], v[112:113], v[112:113]
	v_pk_mul_f32 v[124:125], v[114:115], v[114:115]
	v_cvt_pk_bf16_f32 v112, v116, v117
	v_cvt_pk_bf16_f32 v113, v118, v119
	v_cvt_pk_bf16_f32 v114, v122, v123
	v_cvt_pk_bf16_f32 v115, v124, v125
	v_max_f32_e32 v104, 0, v104
	v_max_f32_e32 v105, 0, v105
	v_lshl_add_u64 v[200:201], v[120:121], 0, s[98:99]
	global_store_dwordx4 v[200:201], v[112:115], off
	s_nop 1
	v_or_b32_e32 v112, 16, v150
	v_pk_mul_f32 v[114:115], v[104:105], v[104:105]
	v_ashrrev_i32_e32 v113, 31, v112
	v_max_f32_e32 v108, 0, v108
	v_max_f32_e32 v109, 0, v109
	v_max_f32_e32 v106, 0, v106
	v_lshlrev_b64 v[112:113], 6, v[112:113]
	v_pk_mul_f32 v[108:109], v[108:109], v[108:109]
	v_max_f32_e32 v104, 0, v110
	v_max_f32_e32 v105, 0, v111
	v_max_f32_e32 v107, 0, v107
	v_pk_mul_f32 v[110:111], v[104:105], v[104:105]
	v_pk_mul_f32 v[116:117], v[106:107], v[106:107]
	v_cvt_pk_bf16_f32 v104, v108, v109
	v_lshl_add_u64 v[108:109], s[78:79], 0, v[112:113]
	v_cvt_pk_bf16_f32 v105, v110, v111
	v_cvt_pk_bf16_f32 v106, v114, v115
	v_cvt_pk_bf16_f32 v107, v116, v117
	v_lshl_add_u64 v[108:109], v[108:109], 0, v[126:127]
	v_max_f32_e32 v96, 0, v96
	v_max_f32_e32 v97, 0, v97
	global_store_dwordx4 v[108:109], v[104:107], off
	s_nop 1
	v_pk_mul_f32 v[104:105], v[96:97], v[96:97]
	v_max_f32_e32 v98, 0, v98
	v_max_f32_e32 v100, 0, v100
	v_max_f32_e32 v101, 0, v101
	v_max_f32_e32 v96, 0, v102
	v_max_f32_e32 v97, 0, v103
	v_max_f32_e32 v99, 0, v99
	v_pk_mul_f32 v[100:101], v[100:101], v[100:101]
	v_pk_mul_f32 v[102:103], v[96:97], v[96:97]
	v_pk_mul_f32 v[106:107], v[98:99], v[98:99]
	v_cvt_pk_bf16_f32 v96, v100, v101
	v_cvt_pk_bf16_f32 v97, v102, v103
	v_cvt_pk_bf16_f32 v98, v104, v105
	v_cvt_pk_bf16_f32 v99, v106, v107
	v_max_f32_e32 v88, 0, v88
	v_max_f32_e32 v89, 0, v89
	v_lshl_add_u64 v[202:203], v[108:109], 0, s[98:99]
	global_store_dwordx4 v[202:203], v[96:99], off
	s_nop 1
	v_or_b32_e32 v96, 32, v150
	v_pk_mul_f32 v[98:99], v[88:89], v[88:89]
	v_ashrrev_i32_e32 v97, 31, v96
	v_max_f32_e32 v92, 0, v92
	v_max_f32_e32 v93, 0, v93
	v_max_f32_e32 v90, 0, v90
	v_lshlrev_b64 v[96:97], 6, v[96:97]
	v_pk_mul_f32 v[92:93], v[92:93], v[92:93]
	v_max_f32_e32 v88, 0, v94
	v_max_f32_e32 v89, 0, v95
	v_max_f32_e32 v91, 0, v91
	v_pk_mul_f32 v[94:95], v[88:89], v[88:89]
	v_pk_mul_f32 v[100:101], v[90:91], v[90:91]
	v_cvt_pk_bf16_f32 v88, v92, v93
	v_lshl_add_u64 v[92:93], s[78:79], 0, v[96:97]
	v_cvt_pk_bf16_f32 v89, v94, v95
	v_cvt_pk_bf16_f32 v90, v98, v99
	v_cvt_pk_bf16_f32 v91, v100, v101
	v_lshl_add_u64 v[92:93], v[92:93], 0, v[126:127]
	v_max_f32_e32 v80, 0, v80
	v_max_f32_e32 v81, 0, v81
	global_store_dwordx4 v[92:93], v[88:91], off
	s_nop 1
	v_pk_mul_f32 v[88:89], v[80:81], v[80:81]
	v_max_f32_e32 v82, 0, v82
	v_max_f32_e32 v84, 0, v84
	v_max_f32_e32 v85, 0, v85
	v_max_f32_e32 v80, 0, v86
	v_max_f32_e32 v81, 0, v87
	v_max_f32_e32 v83, 0, v83
	v_pk_mul_f32 v[84:85], v[84:85], v[84:85]
	v_pk_mul_f32 v[86:87], v[80:81], v[80:81]
	v_pk_mul_f32 v[90:91], v[82:83], v[82:83]
	v_cvt_pk_bf16_f32 v80, v84, v85
	v_cvt_pk_bf16_f32 v81, v86, v87
	v_cvt_pk_bf16_f32 v82, v88, v89
	v_cvt_pk_bf16_f32 v83, v90, v91
	v_max_f32_e32 v72, 0, v72
	v_max_f32_e32 v73, 0, v73
	v_lshl_add_u64 v[204:205], v[92:93], 0, s[98:99]
	global_store_dwordx4 v[204:205], v[80:83], off
	s_nop 1
	v_or_b32_e32 v80, 48, v150
	v_pk_mul_f32 v[82:83], v[72:73], v[72:73]
	v_ashrrev_i32_e32 v81, 31, v80
	v_max_f32_e32 v76, 0, v76
	v_max_f32_e32 v77, 0, v77
	v_max_f32_e32 v74, 0, v74
	v_lshlrev_b64 v[80:81], 6, v[80:81]
	v_pk_mul_f32 v[76:77], v[76:77], v[76:77]
	v_max_f32_e32 v72, 0, v78
	v_max_f32_e32 v73, 0, v79
	v_max_f32_e32 v75, 0, v75
	v_pk_mul_f32 v[78:79], v[72:73], v[72:73]
	v_pk_mul_f32 v[84:85], v[74:75], v[74:75]
	v_cvt_pk_bf16_f32 v72, v76, v77
	v_lshl_add_u64 v[76:77], s[78:79], 0, v[80:81]
	v_cvt_pk_bf16_f32 v73, v78, v79
	v_cvt_pk_bf16_f32 v74, v82, v83
	v_cvt_pk_bf16_f32 v75, v84, v85
	v_lshl_add_u64 v[76:77], v[76:77], 0, v[126:127]
	v_max_f32_e32 v64, 0, v64
	v_max_f32_e32 v65, 0, v65
	global_store_dwordx4 v[76:77], v[72:75], off
	s_nop 1
	v_pk_mul_f32 v[72:73], v[64:65], v[64:65]
	v_max_f32_e32 v66, 0, v66
	v_max_f32_e32 v68, 0, v68
	v_max_f32_e32 v69, 0, v69
	v_max_f32_e32 v64, 0, v70
	v_max_f32_e32 v65, 0, v71
	v_max_f32_e32 v67, 0, v67
	v_pk_mul_f32 v[68:69], v[68:69], v[68:69]
	v_pk_mul_f32 v[70:71], v[64:65], v[64:65]
	v_pk_mul_f32 v[74:75], v[66:67], v[66:67]
	v_cvt_pk_bf16_f32 v64, v68, v69
	v_cvt_pk_bf16_f32 v65, v70, v71
	v_cvt_pk_bf16_f32 v66, v72, v73
	v_cvt_pk_bf16_f32 v67, v74, v75
	v_max_f32_e32 v56, 0, v56
	v_max_f32_e32 v57, 0, v57
	v_lshl_add_u64 v[206:207], v[76:77], 0, s[98:99]
	global_store_dwordx4 v[206:207], v[64:67], off
	s_nop 1
	v_pk_mul_f32 v[64:65], v[56:57], v[56:57]
	v_max_f32_e32 v58, 0, v58
	v_max_f32_e32 v56, 0, v62
	v_max_f32_e32 v57, 0, v63
	v_max_f32_e32 v60, 0, v60
	v_max_f32_e32 v61, 0, v61
	v_max_f32_e32 v59, 0, v59
	v_pk_mul_f32 v[62:63], v[56:57], v[56:57]
	v_pk_mul_f32 v[60:61], v[60:61], v[60:61]
	v_pk_mul_f32 v[66:67], v[58:59], v[58:59]
	v_cvt_pk_bf16_f32 v227, v62, v63
	v_cvt_pk_bf16_f32 v226, v60, v61
	v_cvt_pk_bf16_f32 v228, v64, v65
	v_cvt_pk_bf16_f32 v229, v66, v67
	v_max_f32_e32 v48, 0, v48
	v_max_f32_e32 v49, 0, v49
	v_pk_mul_f32 v[56:57], v[48:49], v[48:49]
	v_max_f32_e32 v50, 0, v50
	v_max_f32_e32 v52, 0, v52
	v_max_f32_e32 v53, 0, v53
	v_max_f32_e32 v48, 0, v54
	v_max_f32_e32 v49, 0, v55
	v_max_f32_e32 v51, 0, v51
	v_pk_mul_f32 v[52:53], v[52:53], v[52:53]
	v_pk_mul_f32 v[54:55], v[48:49], v[48:49]
	v_pk_mul_f32 v[58:59], v[50:51], v[50:51]
	v_cvt_pk_bf16_f32 v230, v52, v53
	v_cvt_pk_bf16_f32 v231, v54, v55
	v_cvt_pk_bf16_f32 v232, v56, v57
	v_cvt_pk_bf16_f32 v233, v58, v59
	v_max_f32_e32 v40, 0, v40
	v_max_f32_e32 v41, 0, v41
	v_pk_mul_f32 v[48:49], v[40:41], v[40:41]
	v_max_f32_e32 v42, 0, v42
	v_max_f32_e32 v40, 0, v46
	v_max_f32_e32 v41, 0, v47
	v_max_f32_e32 v44, 0, v44
	v_max_f32_e32 v45, 0, v45
	v_max_f32_e32 v43, 0, v43
	v_pk_mul_f32 v[46:47], v[40:41], v[40:41]
	v_pk_mul_f32 v[44:45], v[44:45], v[44:45]
	v_pk_mul_f32 v[50:51], v[42:43], v[42:43]
	v_cvt_pk_bf16_f32 v235, v46, v47
	v_cvt_pk_bf16_f32 v234, v44, v45
	v_cvt_pk_bf16_f32 v236, v48, v49
	v_cvt_pk_bf16_f32 v237, v50, v51
	v_max_f32_e32 v32, 0, v32
	v_max_f32_e32 v33, 0, v33
	v_pk_mul_f32 v[40:41], v[32:33], v[32:33]
	v_max_f32_e32 v34, 0, v34
	v_max_f32_e32 v36, 0, v36
	v_max_f32_e32 v37, 0, v37
	v_max_f32_e32 v32, 0, v38
	v_max_f32_e32 v33, 0, v39
	v_max_f32_e32 v35, 0, v35
	v_pk_mul_f32 v[36:37], v[36:37], v[36:37]
	v_pk_mul_f32 v[38:39], v[32:33], v[32:33]
	v_pk_mul_f32 v[42:43], v[34:35], v[34:35]
	v_cvt_pk_bf16_f32 v238, v36, v37
	v_cvt_pk_bf16_f32 v239, v38, v39
	v_cvt_pk_bf16_f32 v240, v40, v41
	v_cvt_pk_bf16_f32 v241, v42, v43
	v_max_f32_e32 v24, 0, v24
	v_max_f32_e32 v25, 0, v25
	v_pk_mul_f32 v[32:33], v[24:25], v[24:25]
	v_max_f32_e32 v26, 0, v26
	v_max_f32_e32 v24, 0, v30
	v_max_f32_e32 v25, 0, v31
	v_max_f32_e32 v28, 0, v28
	v_max_f32_e32 v29, 0, v29
	v_max_f32_e32 v27, 0, v27
	v_pk_mul_f32 v[30:31], v[24:25], v[24:25]
	v_pk_mul_f32 v[28:29], v[28:29], v[28:29]
	v_pk_mul_f32 v[34:35], v[26:27], v[26:27]
	v_cvt_pk_bf16_f32 v243, v30, v31
	v_cvt_pk_bf16_f32 v242, v28, v29
	v_cvt_pk_bf16_f32 v244, v32, v33
	v_cvt_pk_bf16_f32 v245, v34, v35
	v_max_f32_e32 v16, 0, v16
	v_max_f32_e32 v17, 0, v17
	v_pk_mul_f32 v[24:25], v[16:17], v[16:17]
	v_max_f32_e32 v18, 0, v18
	v_max_f32_e32 v20, 0, v20
	v_max_f32_e32 v21, 0, v21
	v_max_f32_e32 v16, 0, v22
	v_max_f32_e32 v17, 0, v23
	v_max_f32_e32 v19, 0, v19
	v_pk_mul_f32 v[20:21], v[20:21], v[20:21]
	v_pk_mul_f32 v[22:23], v[16:17], v[16:17]
	v_pk_mul_f32 v[26:27], v[18:19], v[18:19]
	v_cvt_pk_bf16_f32 v246, v20, v21
	v_cvt_pk_bf16_f32 v247, v22, v23
	v_cvt_pk_bf16_f32 v248, v24, v25
	v_cvt_pk_bf16_f32 v249, v26, v27
	v_max_f32_e32 v8, 0, v8
	v_max_f32_e32 v9, 0, v9
	v_pk_mul_f32 v[16:17], v[8:9], v[8:9]
	v_max_f32_e32 v10, 0, v10
	v_max_f32_e32 v8, 0, v14
	v_max_f32_e32 v9, 0, v15
	v_max_f32_e32 v12, 0, v12
	v_max_f32_e32 v13, 0, v13
	v_max_f32_e32 v11, 0, v11
	v_pk_mul_f32 v[14:15], v[8:9], v[8:9]
	v_pk_mul_f32 v[12:13], v[12:13], v[12:13]
	v_pk_mul_f32 v[18:19], v[10:11], v[10:11]
	v_cvt_pk_bf16_f32 v251, v14, v15
	v_cvt_pk_bf16_f32 v250, v12, v13
	v_cvt_pk_bf16_f32 v252, v16, v17
	v_cvt_pk_bf16_f32 v253, v18, v19
	v_max_f32_e32 v0, 0, v0
	v_max_f32_e32 v1, 0, v1
	v_pk_mul_f32 v[8:9], v[0:1], v[0:1]
	v_max_f32_e32 v2, 0, v2
	v_max_f32_e32 v4, 0, v4
	v_max_f32_e32 v5, 0, v5
	v_max_f32_e32 v0, 0, v6
	v_max_f32_e32 v1, 0, v7
	v_max_f32_e32 v3, 0, v3
	v_pk_mul_f32 v[4:5], v[4:5], v[4:5]
	v_pk_mul_f32 v[6:7], v[0:1], v[0:1]
	v_pk_mul_f32 v[10:11], v[2:3], v[2:3]
	v_cvt_pk_bf16_f32 v140, v4, v5
	v_cvt_pk_bf16_f32 v141, v6, v7
	v_cvt_pk_bf16_f32 v142, v8, v9
	v_cvt_pk_bf16_f32 v143, v10, v11
	s_andn2_b64 vcc, exec, s[4:5]
	s_mov_b64 s[4:5], -1
	s_mov_b32 s100, 1
	s_cbranch_vccnz .LBB0_869
	s_andn2_b64 vcc, exec, s[6:7]
	s_cbranch_vccnz .LBB0_868
	s_barrier
	s_branch .LBB0_868
.LBB0_883:
	global_store_dwordx4 v255, v[226:229], s[16:17]
	global_store_dwordx4 v255, v[230:233], s[18:19]
	global_store_dwordx4 v255, v[234:237], s[16:17] offset:1024
	global_store_dwordx4 v255, v[238:241], s[18:19] offset:1024
	global_store_dwordx4 v255, v[242:245], s[16:17] offset:2048
	global_store_dwordx4 v255, v[246:249], s[18:19] offset:2048
	global_store_dwordx4 v255, v[250:253], s[16:17] offset:3072
	global_store_dwordx4 v255, v[140:143], s[18:19] offset:3072
	s_waitcnt vmcnt(0)
	s_barrier

	.amdhsa_kernel _Z10fwd_kernel4Args
		.amdhsa_group_segment_fixed_size 0
		.amdhsa_private_segment_fixed_size 0
		.amdhsa_kernarg_size 432
		.amdhsa_user_sgpr_count 2
		.amdhsa_user_sgpr_dispatch_ptr 0
		.amdhsa_user_sgpr_queue_ptr 0
		.amdhsa_user_sgpr_kernarg_segment_ptr 1
		.amdhsa_user_sgpr_dispatch_id 0
		.amdhsa_user_sgpr_kernarg_preload_length 0
		.amdhsa_user_sgpr_kernarg_preload_offset 0
		.amdhsa_user_sgpr_private_segment_size 0
		.amdhsa_uses_dynamic_stack 0
		.amdhsa_enable_private_segment 0
		.amdhsa_system_sgpr_workgroup_id_x 1
		.amdhsa_system_sgpr_workgroup_id_y 0
		.amdhsa_system_sgpr_workgroup_id_z 0
		.amdhsa_system_sgpr_workgroup_info 0
		.amdhsa_system_vgpr_workitem_id 2
		.amdhsa_next_free_vgpr 256
		.amdhsa_next_free_sgpr 102
		.amdhsa_accum_offset 256
		.amdhsa_reserve_vcc 1
		.amdhsa_float_round_mode_32 0
		.amdhsa_float_round_mode_16_64 0
		.amdhsa_float_denorm_mode_32 3
		.amdhsa_float_denorm_mode_16_64 3
		.amdhsa_dx10_clamp 1
		.amdhsa_ieee_mode 1
		.amdhsa_fp16_overflow 0
		.amdhsa_tg_split 0
		.amdhsa_exception_fp_ieee_invalid_op 0
		.amdhsa_exception_fp_denorm_src 0
		.amdhsa_exception_fp_ieee_div_zero 0
		.amdhsa_exception_fp_ieee_overflow 0
		.amdhsa_exception_fp_ieee_underflow 0
		.amdhsa_exception_fp_ieee_inexact 0
		.amdhsa_exception_int_div_zero 0
	.end_amdhsa_kernel

amdhsa.kernels:
  - .agpr_count:     0
    .args:
      - .offset:         0
        .size:           176
        .value_kind:     by_value
      - .offset:         176
        .size:           4
        .value_kind:     hidden_block_count_x
      - .offset:         180
        .size:           4
        .value_kind:     hidden_block_count_y
      - .offset:         184
        .size:           4
        .value_kind:     hidden_block_count_z
      - .offset:         188
        .size:           2
        .value_kind:     hidden_group_size_x
      - .offset:         190
        .size:           2
        .value_kind:     hidden_group_size_y
      - .offset:         192
        .size:           2
        .value_kind:     hidden_group_size_z
      - .offset:         194
        .size:           2
        .value_kind:     hidden_remainder_x
      - .offset:         196
        .size:           2
        .value_kind:     hidden_remainder_y
      - .offset:         198
        .size:           2
        .value_kind:     hidden_remainder_z
      - .offset:         216
        .size:           8
        .value_kind:     hidden_global_offset_x
      - .offset:         224
        .size:           8
        .value_kind:     hidden_global_offset_y
      - .offset:         232
        .size:           8
        .value_kind:     hidden_global_offset_z
      - .offset:         240
        .size:           2
        .value_kind:     hidden_grid_dims
      - .offset:         264
        .size:           8
        .value_kind:     hidden_multigrid_sync_arg
      - .offset:         296
        .size:           4
        .value_kind:     hidden_dynamic_lds_size
    .group_segment_fixed_size: 0
    .kernarg_segment_align: 8
    .kernarg_segment_size: 432
    .language:       OpenCL C
    .language_version:
      - 2
      - 0
    .max_flat_workgroup_size: 512
    .name:           _Z10fwd_kernel4Args
    .private_segment_fixed_size: 0
    .sgpr_count:     108
    .sgpr_spill_count: 53
    .symbol:         _Z10fwd_kernel4Args.kd
    .uniform_work_group_size: 1
    .uses_dynamic_stack: false
    .vgpr_count:     256
    .vgpr_spill_count: 0
    .wavefront_size: 64
